# v67 plus MLP2A/B as one hand-written 256x256 16x16x32 tile per workgroup
# speedup vs baseline: 1.0122x; 1.0028x over previous
.LBB0_55:
	s_waitcnt lgkmcnt(0)
	s_lshl_b64 s[36:37], s[28:29], 13
	s_add_u32 s36, s36, s34
	s_addc_u32 s37, s37, s35
	s_lshl_b32 s65, s52, 3
	s_sub_i32 s65, s24, s65
	s_lshl_b32 s28, s65, 7
	s_lshl_b32 s65, s28, 13
	s_add_u32 s98, s50, s65
	s_addc_u32 s99, s51, 0
	v_readfirstlane_b32 s65, v200
	s_lshr_b32 s65, s65, 6
	s_lshl_b32 s25, s65, 11
	s_add_u32 s25, s25, 16
	s_lshl_b32 s65, s65, 18
	s_add_u32 s36, s36, s65
	s_addc_u32 s37, s37, 0
	s_add_u32 s98, s98, s65
	s_addc_u32 s99, s99, 0
	v_bfe_u32 v173, v200, 4, 2
	v_sub_u32_e32 v173, 0, v173
	v_and_b32_e32 v173, 3, v173
	v_and_b32_e32 v172, 3, v200
	v_xor_b32_e32 v172, v172, v173
	v_bfe_u32 v173, v200, 2, 4
	v_lshlrev_b32_e32 v173, 13, v173
	v_lshl_or_b32 v170, v172, 4, v173
	v_add_u32_e32 v171, 0x20000, v170
	v_bfe_u32 v172, v200, 2, 2
	v_sub_u32_e32 v172, 0, v172
	v_and_b32_e32 v172, 3, v172
	v_bfe_u32 v173, v200, 4, 2
	v_xor_b32_e32 v172, v172, v173
	v_and_b32_e32 v173, 15, v200
	v_bfe_u32 v174, v200, 8, 1
	v_lshl_or_b32 v174, v174, 7, v173
	v_lshlrev_b32_e32 v174, 6, v174
	v_lshl_or_b32 v164, v172, 4, v174
	v_bfe_u32 v174, v200, 6, 2
	v_lshl_or_b32 v174, v174, 6, v173
	v_lshlrev_b32_e32 v174, 6, v174
	v_lshl_or_b32 v165, v172, 4, v174
	v_add_u32_e32 v165, 0x4000, v165
	v_bfe_u32 v172, v200, 6, 2
	v_bfe_u32 v173, v200, 4, 2
	v_lshlrev_b32_e32 v172, 6, v172
	v_lshl_or_b32 v172, v173, 2, v172
	v_add_u32_e32 v172, s28, v172
	v_lshlrev_b32_e32 v172, 2, v172
	global_load_dwordx4 v[132:135], v172, s[44:45]
	global_load_dwordx4 v[136:139], v172, s[44:45] offset:64
	global_load_dwordx4 v[140:143], v172, s[44:45] offset:128
	global_load_dwordx4 v[144:147], v172, s[44:45] offset:192
	s_mov_b32 s32, s25
	s_mov_b32 m0, s32
	s_nop 0
	global_load_lds_dwordx4 v170, s[36:37]
	s_add_u32 m0, s32, 0x400
	s_nop 0
	global_load_lds_dwordx4 v171, s[36:37]
	s_add_u32 m0, s32, 0x4000
	s_nop 0
	global_load_lds_dwordx4 v170, s[98:99]
	s_add_u32 m0, s32, 0x4400
	s_nop 0
	global_load_lds_dwordx4 v171, s[98:99]
	s_add_u32 s36, s36, 64
	s_addc_u32 s37, s37, 0
	s_add_u32 s98, s98, 64
	s_addc_u32 s99, s99, 0
	s_add_u32 s32, s25, 0x8000
	s_mov_b32 m0, s32
	s_nop 0
	global_load_lds_dwordx4 v170, s[36:37]
	s_add_u32 m0, s32, 0x400
	s_nop 0
	global_load_lds_dwordx4 v171, s[36:37]
	s_add_u32 m0, s32, 0x4000
	s_nop 0
	global_load_lds_dwordx4 v170, s[98:99]
	s_add_u32 m0, s32, 0x4400
	s_nop 0
	global_load_lds_dwordx4 v171, s[98:99]
	s_add_u32 s36, s36, 64
	s_addc_u32 s37, s37, 0
	s_add_u32 s98, s98, 64
	s_addc_u32 s99, s99, 0
	s_add_u32 s32, s25, 0x10000
	s_mov_b32 m0, s32
	s_nop 0
	global_load_lds_dwordx4 v170, s[36:37]
	s_add_u32 m0, s32, 0x400
	s_nop 0
	global_load_lds_dwordx4 v171, s[36:37]
	s_add_u32 m0, s32, 0x4000
	s_nop 0
	global_load_lds_dwordx4 v170, s[98:99]
	s_add_u32 m0, s32, 0x4400
	s_nop 0
	global_load_lds_dwordx4 v171, s[98:99]
	s_add_u32 s36, s36, 64
	s_addc_u32 s37, s37, 0
	s_add_u32 s98, s98, 64
	s_addc_u32 s99, s99, 0
	s_add_u32 s32, s25, 0x18000
	s_mov_b32 m0, s32
	s_nop 0
	global_load_lds_dwordx4 v170, s[36:37]
	s_add_u32 m0, s32, 0x400
	s_nop 0
	global_load_lds_dwordx4 v171, s[36:37]
	s_add_u32 m0, s32, 0x4000
	s_nop 0
	global_load_lds_dwordx4 v170, s[98:99]
	s_add_u32 m0, s32, 0x4400
	s_nop 0
	global_load_lds_dwordx4 v171, s[98:99]
	s_add_u32 s36, s36, 64
	s_addc_u32 s37, s37, 0
	s_add_u32 s98, s98, 64
	s_addc_u32 s99, s99, 0
	s_waitcnt vmcnt(16)
	v_mov_b32_e32 v4, v132
	v_mov_b32_e32 v5, v133
	v_mov_b32_e32 v6, v134
	v_mov_b32_e32 v7, v135
	v_mov_b32_e32 v8, v136
	v_mov_b32_e32 v9, v137
	v_mov_b32_e32 v10, v138
	v_mov_b32_e32 v11, v139
	v_mov_b32_e32 v12, v140
	v_mov_b32_e32 v13, v141
	v_mov_b32_e32 v14, v142
	v_mov_b32_e32 v15, v143
	v_mov_b32_e32 v16, v144
	v_mov_b32_e32 v17, v145
	v_mov_b32_e32 v18, v146
	v_mov_b32_e32 v19, v147
	v_mov_b32_e32 v20, v132
	v_mov_b32_e32 v21, v133
	v_mov_b32_e32 v22, v134
	v_mov_b32_e32 v23, v135
	v_mov_b32_e32 v24, v136
	v_mov_b32_e32 v25, v137
	v_mov_b32_e32 v26, v138
	v_mov_b32_e32 v27, v139
	v_mov_b32_e32 v28, v140
	v_mov_b32_e32 v29, v141
	v_mov_b32_e32 v30, v142
	v_mov_b32_e32 v31, v143
	v_mov_b32_e32 v32, v144
	v_mov_b32_e32 v33, v145
	v_mov_b32_e32 v34, v146
	v_mov_b32_e32 v35, v147
	v_mov_b32_e32 v36, v132
	v_mov_b32_e32 v37, v133
	v_mov_b32_e32 v38, v134
	v_mov_b32_e32 v39, v135
	v_mov_b32_e32 v40, v136
	v_mov_b32_e32 v41, v137
	v_mov_b32_e32 v42, v138
	v_mov_b32_e32 v43, v139
	v_mov_b32_e32 v44, v140
	v_mov_b32_e32 v45, v141
	v_mov_b32_e32 v46, v142
	v_mov_b32_e32 v47, v143
	v_mov_b32_e32 v48, v144
	v_mov_b32_e32 v49, v145
	v_mov_b32_e32 v50, v146
	v_mov_b32_e32 v51, v147
	v_mov_b32_e32 v52, v132
	v_mov_b32_e32 v53, v133
	v_mov_b32_e32 v54, v134
	v_mov_b32_e32 v55, v135
	v_mov_b32_e32 v56, v136
	v_mov_b32_e32 v57, v137
	v_mov_b32_e32 v58, v138
	v_mov_b32_e32 v59, v139
	v_mov_b32_e32 v60, v140
	v_mov_b32_e32 v61, v141
	v_mov_b32_e32 v62, v142
	v_mov_b32_e32 v63, v143
	v_mov_b32_e32 v64, v144
	v_mov_b32_e32 v65, v145
	v_mov_b32_e32 v66, v146
	v_mov_b32_e32 v67, v147
	v_mov_b32_e32 v68, v132
	v_mov_b32_e32 v69, v133
	v_mov_b32_e32 v70, v134
	v_mov_b32_e32 v71, v135
	v_mov_b32_e32 v72, v136
	v_mov_b32_e32 v73, v137
	v_mov_b32_e32 v74, v138
	v_mov_b32_e32 v75, v139
	v_mov_b32_e32 v76, v140
	v_mov_b32_e32 v77, v141
	v_mov_b32_e32 v78, v142
	v_mov_b32_e32 v79, v143
	v_mov_b32_e32 v80, v144
	v_mov_b32_e32 v81, v145
	v_mov_b32_e32 v82, v146
	v_mov_b32_e32 v83, v147
	v_mov_b32_e32 v84, v132
	v_mov_b32_e32 v85, v133
	v_mov_b32_e32 v86, v134
	v_mov_b32_e32 v87, v135
	v_mov_b32_e32 v88, v136
	v_mov_b32_e32 v89, v137
	v_mov_b32_e32 v90, v138
	v_mov_b32_e32 v91, v139
	v_mov_b32_e32 v92, v140
	v_mov_b32_e32 v93, v141
	v_mov_b32_e32 v94, v142
	v_mov_b32_e32 v95, v143
	v_mov_b32_e32 v96, v144
	v_mov_b32_e32 v97, v145
	v_mov_b32_e32 v98, v146
	v_mov_b32_e32 v99, v147
	v_mov_b32_e32 v100, v132
	v_mov_b32_e32 v101, v133
	v_mov_b32_e32 v102, v134
	v_mov_b32_e32 v103, v135
	v_mov_b32_e32 v104, v136
	v_mov_b32_e32 v105, v137
	v_mov_b32_e32 v106, v138
	v_mov_b32_e32 v107, v139
	v_mov_b32_e32 v108, v140
	v_mov_b32_e32 v109, v141
	v_mov_b32_e32 v110, v142
	v_mov_b32_e32 v111, v143
	v_mov_b32_e32 v112, v144
	v_mov_b32_e32 v113, v145
	v_mov_b32_e32 v114, v146
	v_mov_b32_e32 v115, v147
	v_mov_b32_e32 v116, v132
	v_mov_b32_e32 v117, v133
	v_mov_b32_e32 v118, v134
	v_mov_b32_e32 v119, v135
	v_mov_b32_e32 v120, v136
	v_mov_b32_e32 v121, v137
	v_mov_b32_e32 v122, v138
	v_mov_b32_e32 v123, v139
	v_mov_b32_e32 v124, v140
	v_mov_b32_e32 v125, v141
	v_mov_b32_e32 v126, v142
	v_mov_b32_e32 v127, v143
	v_mov_b32_e32 v128, v144
	v_mov_b32_e32 v129, v145
	v_mov_b32_e32 v130, v146
	v_mov_b32_e32 v131, v147
	s_waitcnt vmcnt(12)
	s_barrier
	s_mov_b32 s31, 0
	s_mov_b32 s53, 0
	s_nop 1
	v_add_u32_e32 v168, s31, v165
	v_add_u32_e32 v169, s31, v164
	ds_read_b128 v[132:135], v168 offset:16
	ds_read_b128 v[136:139], v168 offset:1040
	ds_read_b128 v[140:143], v168 offset:2064
	ds_read_b128 v[144:147], v168 offset:3088
	ds_read_b128 v[184:187], v169 offset:16
	ds_read_b128 v[188:191], v169 offset:1040
	ds_read_b128 v[192:195], v169 offset:2064
	ds_read_b128 v[196:199], v169 offset:3088
	s_waitcnt lgkmcnt(0)

.LBB0_704:
	s_waitcnt lgkmcnt(0)
	s_lshl_b64 s[50:51], s[30:31], 13
	s_add_u32 s50, s50, s36
	s_addc_u32 s51, s51, s37
	s_lshl_b32 s65, s52, 3
	s_sub_i32 s65, s24, s65
	s_lshl_b32 s30, s65, 7
	s_lshl_b32 s65, s30, 13
	s_add_u32 s54, s48, s65
	s_addc_u32 s55, s49, 0
	v_readfirstlane_b32 s65, v200
	s_lshr_b32 s65, s65, 6
	s_lshl_b32 s25, s65, 11
	s_add_u32 s25, s25, 16
	s_lshl_b32 s65, s65, 18
	s_add_u32 s50, s50, s65
	s_addc_u32 s51, s51, 0
	s_add_u32 s54, s54, s65
	s_addc_u32 s55, s55, 0
	v_bfe_u32 v173, v200, 4, 2
	v_sub_u32_e32 v173, 0, v173
	v_and_b32_e32 v173, 3, v173
	v_and_b32_e32 v172, 3, v200
	v_xor_b32_e32 v172, v172, v173
	v_bfe_u32 v173, v200, 2, 4
	v_lshlrev_b32_e32 v173, 13, v173
	v_lshl_or_b32 v170, v172, 4, v173
	v_add_u32_e32 v171, 0x20000, v170
	v_bfe_u32 v172, v200, 2, 2
	v_sub_u32_e32 v172, 0, v172
	v_and_b32_e32 v172, 3, v172
	v_bfe_u32 v173, v200, 4, 2
	v_xor_b32_e32 v172, v172, v173
	v_and_b32_e32 v173, 15, v200
	v_bfe_u32 v174, v200, 8, 1
	v_lshl_or_b32 v174, v174, 7, v173
	v_lshlrev_b32_e32 v174, 6, v174
	v_lshl_or_b32 v164, v172, 4, v174
	v_bfe_u32 v174, v200, 6, 2
	v_lshl_or_b32 v174, v174, 6, v173
	v_lshlrev_b32_e32 v174, 6, v174
	v_lshl_or_b32 v165, v172, 4, v174
	v_add_u32_e32 v165, 0x4000, v165
	v_bfe_u32 v172, v200, 6, 2
	v_bfe_u32 v173, v200, 4, 2
	v_lshlrev_b32_e32 v172, 6, v172
	v_lshl_or_b32 v172, v173, 2, v172
	v_add_u32_e32 v172, s30, v172
	v_lshlrev_b32_e32 v172, 2, v172
	global_load_dwordx4 v[132:135], v172, s[42:43]
	global_load_dwordx4 v[136:139], v172, s[42:43] offset:64
	global_load_dwordx4 v[140:143], v172, s[42:43] offset:128
	global_load_dwordx4 v[144:147], v172, s[42:43] offset:192
	s_mov_b32 s35, s25
	s_mov_b32 m0, s35
	s_nop 0
	global_load_lds_dwordx4 v170, s[50:51]
	s_add_u32 m0, s35, 0x400
	s_nop 0
	global_load_lds_dwordx4 v171, s[50:51]
	s_add_u32 m0, s35, 0x4000
	s_nop 0
	global_load_lds_dwordx4 v170, s[54:55]
	s_add_u32 m0, s35, 0x4400
	s_nop 0
	global_load_lds_dwordx4 v171, s[54:55]
	s_add_u32 s50, s50, 64
	s_addc_u32 s51, s51, 0
	s_add_u32 s54, s54, 64
	s_addc_u32 s55, s55, 0
	s_add_u32 s35, s25, 0x8000
	s_mov_b32 m0, s35
	s_nop 0
	global_load_lds_dwordx4 v170, s[50:51]
	s_add_u32 m0, s35, 0x400
	s_nop 0
	global_load_lds_dwordx4 v171, s[50:51]
	s_add_u32 m0, s35, 0x4000
	s_nop 0
	global_load_lds_dwordx4 v170, s[54:55]
	s_add_u32 m0, s35, 0x4400
	s_nop 0
	global_load_lds_dwordx4 v171, s[54:55]
	s_add_u32 s50, s50, 64
	s_addc_u32 s51, s51, 0
	s_add_u32 s54, s54, 64
	s_addc_u32 s55, s55, 0
	s_add_u32 s35, s25, 0x10000
	s_mov_b32 m0, s35
	s_nop 0
	global_load_lds_dwordx4 v170, s[50:51]
	s_add_u32 m0, s35, 0x400
	s_nop 0
	global_load_lds_dwordx4 v171, s[50:51]
	s_add_u32 m0, s35, 0x4000
	s_nop 0
	global_load_lds_dwordx4 v170, s[54:55]
	s_add_u32 m0, s35, 0x4400
	s_nop 0
	global_load_lds_dwordx4 v171, s[54:55]
	s_add_u32 s50, s50, 64
	s_addc_u32 s51, s51, 0
	s_add_u32 s54, s54, 64
	s_addc_u32 s55, s55, 0
	s_add_u32 s35, s25, 0x18000
	s_mov_b32 m0, s35
	s_nop 0
	global_load_lds_dwordx4 v170, s[50:51]
	s_add_u32 m0, s35, 0x400
	s_nop 0
	global_load_lds_dwordx4 v171, s[50:51]
	s_add_u32 m0, s35, 0x4000
	s_nop 0
	global_load_lds_dwordx4 v170, s[54:55]
	s_add_u32 m0, s35, 0x4400
	s_nop 0
	global_load_lds_dwordx4 v171, s[54:55]
	s_add_u32 s50, s50, 64
	s_addc_u32 s51, s51, 0
	s_add_u32 s54, s54, 64
	s_addc_u32 s55, s55, 0
	s_waitcnt vmcnt(16)
	v_mov_b32_e32 v4, v132
	v_mov_b32_e32 v5, v133
	v_mov_b32_e32 v6, v134
	v_mov_b32_e32 v7, v135
	v_mov_b32_e32 v8, v136
	v_mov_b32_e32 v9, v137
	v_mov_b32_e32 v10, v138
	v_mov_b32_e32 v11, v139
	v_mov_b32_e32 v12, v140
	v_mov_b32_e32 v13, v141
	v_mov_b32_e32 v14, v142
	v_mov_b32_e32 v15, v143
	v_mov_b32_e32 v16, v144
	v_mov_b32_e32 v17, v145
	v_mov_b32_e32 v18, v146
	v_mov_b32_e32 v19, v147
	v_mov_b32_e32 v20, v132
	v_mov_b32_e32 v21, v133
	v_mov_b32_e32 v22, v134
	v_mov_b32_e32 v23, v135
	v_mov_b32_e32 v24, v136
	v_mov_b32_e32 v25, v137
	v_mov_b32_e32 v26, v138
	v_mov_b32_e32 v27, v139
	v_mov_b32_e32 v28, v140
	v_mov_b32_e32 v29, v141
	v_mov_b32_e32 v30, v142
	v_mov_b32_e32 v31, v143
	v_mov_b32_e32 v32, v144
	v_mov_b32_e32 v33, v145
	v_mov_b32_e32 v34, v146
	v_mov_b32_e32 v35, v147
	v_mov_b32_e32 v36, v132
	v_mov_b32_e32 v37, v133
	v_mov_b32_e32 v38, v134
	v_mov_b32_e32 v39, v135
	v_mov_b32_e32 v40, v136
	v_mov_b32_e32 v41, v137
	v_mov_b32_e32 v42, v138
	v_mov_b32_e32 v43, v139
	v_mov_b32_e32 v44, v140
	v_mov_b32_e32 v45, v141
	v_mov_b32_e32 v46, v142
	v_mov_b32_e32 v47, v143
	v_mov_b32_e32 v48, v144
	v_mov_b32_e32 v49, v145
	v_mov_b32_e32 v50, v146
	v_mov_b32_e32 v51, v147
	v_mov_b32_e32 v52, v132
	v_mov_b32_e32 v53, v133
	v_mov_b32_e32 v54, v134
	v_mov_b32_e32 v55, v135
	v_mov_b32_e32 v56, v136
	v_mov_b32_e32 v57, v137
	v_mov_b32_e32 v58, v138
	v_mov_b32_e32 v59, v139
	v_mov_b32_e32 v60, v140
	v_mov_b32_e32 v61, v141
	v_mov_b32_e32 v62, v142
	v_mov_b32_e32 v63, v143
	v_mov_b32_e32 v64, v144
	v_mov_b32_e32 v65, v145
	v_mov_b32_e32 v66, v146
	v_mov_b32_e32 v67, v147
	v_mov_b32_e32 v68, v132
	v_mov_b32_e32 v69, v133
	v_mov_b32_e32 v70, v134
	v_mov_b32_e32 v71, v135
	v_mov_b32_e32 v72, v136
	v_mov_b32_e32 v73, v137
	v_mov_b32_e32 v74, v138
	v_mov_b32_e32 v75, v139
	v_mov_b32_e32 v76, v140
	v_mov_b32_e32 v77, v141
	v_mov_b32_e32 v78, v142
	v_mov_b32_e32 v79, v143
	v_mov_b32_e32 v80, v144
	v_mov_b32_e32 v81, v145
	v_mov_b32_e32 v82, v146
	v_mov_b32_e32 v83, v147
	v_mov_b32_e32 v84, v132
	v_mov_b32_e32 v85, v133
	v_mov_b32_e32 v86, v134
	v_mov_b32_e32 v87, v135
	v_mov_b32_e32 v88, v136
	v_mov_b32_e32 v89, v137
	v_mov_b32_e32 v90, v138
	v_mov_b32_e32 v91, v139
	v_mov_b32_e32 v92, v140
	v_mov_b32_e32 v93, v141
	v_mov_b32_e32 v94, v142
	v_mov_b32_e32 v95, v143
	v_mov_b32_e32 v96, v144
	v_mov_b32_e32 v97, v145
	v_mov_b32_e32 v98, v146
	v_mov_b32_e32 v99, v147
	v_mov_b32_e32 v100, v132
	v_mov_b32_e32 v101, v133
	v_mov_b32_e32 v102, v134
	v_mov_b32_e32 v103, v135
	v_mov_b32_e32 v104, v136
	v_mov_b32_e32 v105, v137
	v_mov_b32_e32 v106, v138
	v_mov_b32_e32 v107, v139
	v_mov_b32_e32 v108, v140
	v_mov_b32_e32 v109, v141
	v_mov_b32_e32 v110, v142
	v_mov_b32_e32 v111, v143
	v_mov_b32_e32 v112, v144
	v_mov_b32_e32 v113, v145
	v_mov_b32_e32 v114, v146
	v_mov_b32_e32 v115, v147
	v_mov_b32_e32 v116, v132
	v_mov_b32_e32 v117, v133
	v_mov_b32_e32 v118, v134
	v_mov_b32_e32 v119, v135
	v_mov_b32_e32 v120, v136
	v_mov_b32_e32 v121, v137
	v_mov_b32_e32 v122, v138
	v_mov_b32_e32 v123, v139
	v_mov_b32_e32 v124, v140
	v_mov_b32_e32 v125, v141
	v_mov_b32_e32 v126, v142
	v_mov_b32_e32 v127, v143
	v_mov_b32_e32 v128, v144
	v_mov_b32_e32 v129, v145
	v_mov_b32_e32 v130, v146
	v_mov_b32_e32 v131, v147
	s_waitcnt vmcnt(12)
	s_barrier
	s_mov_b32 s32, 0
	s_mov_b32 s53, 0
	s_nop 1
	v_add_u32_e32 v168, s32, v165
	v_add_u32_e32 v169, s32, v164
	ds_read_b128 v[132:135], v168 offset:16
	ds_read_b128 v[136:139], v168 offset:1040
	ds_read_b128 v[140:143], v168 offset:2064
	ds_read_b128 v[144:147], v168 offset:3088
	ds_read_b128 v[184:187], v169 offset:16
	ds_read_b128 v[188:191], v169 offset:1040
	ds_read_b128 v[192:195], v169 offset:2064
	ds_read_b128 v[196:199], v169 offset:3088
	s_waitcnt lgkmcnt(0)
